# P4 scan: all chunk-state loads of both ids issued up front, serial fma/store chain with counted vmcnt waits
# baseline (speedup 1.0000x reference)
; __device__ __forceinline__ void unpack8(u32x4 r, float* f) { f[0] = bflo(r.x); f[1] = bfhi(r.x); f[2] = bflo(r.y); f[3] = bfhi(r.y); f[4] = bflo(r.z); f[5] = bfhi(r.z); f[6] = bflo(r.w); f[7] = bfhi(r.w); }
; __device__ __forceinline__ u32x4 pack8(const float* f) { u32x4 o; o.x = pk2(f[0], f[1]); o.y = pk2(f[2], f[3]); o.z = pk2(f[4], f[5]); o.w = pk2(f[6], f[7]); return o; }
;     __device__ __forceinline__ PT() { out = (float*)(__attribute__((address_space(1))) float*)ptab_get(23); ws = (unsigned char*)(__attribute__((address_space(1))) unsigned char*)ptab_get(24); }
; __device__ __forceinline__ void phase_scan(const PT& p, int tid) {
;     unsigned char* ws = p.ws; const bf16* ST = (const bf16*)(ws + WS_STATES); const float* CD = (const float*)(ws + WS_CD); bf16* PV = (bf16*)((unsigned char*)p.out + DO_PREV);
;     for (int id = blockIdx.x * 512 + tid; id < NBATCH * 32 * 64 * 16; id += gridDim.x * 512) {
;         const int b = id >> 15, rem = id & 32767, hh = rem >> 10;
;         float run[8];
; #pragma unroll
;         for (int j = 0; j < 8; ++j) run[j] = 0.f;
; #pragma unroll
;         for (int c = 0; c < 16; ++c) {
;             const size_t off = ((size_t)(b * 16 + c) * 32 * 64 * 16 + rem) * 8;
;             *(u32x4*)(PV + off) = pack8(run);
;             if (c < 15) { float s[8]; unpack8(*(const u32x4*)(ST + off), s); const float cd = CD[(b * 16 + c) * 32 + hh];
; #pragma unroll
;                 for (int j = 0; j < 8; ++j) run[j] = run[j] * cd + s[j]; }
;         }
;     }
; }
.LBB0_427:
	s_or_b64 exec, exec, s[0:1]
	s_waitcnt lgkmcnt(0)
	v_mov_b32_e32 v0, 0x23eb8
	s_barrier
	ds_read_b64 v[0:1], v0
	v_mov_b32_e32 v2, 0x23ec0
	ds_read_b64 v[2:3], v2
	s_mov_b32 s2, 0x40000
	s_waitcnt lgkmcnt(1)
	v_readfirstlane_b32 s0, v0
	v_mov_b32_e32 v0, v196
	v_readfirstlane_b32 s1, v1
	v_add_u32_e32 v16, s51, v0
	s_waitcnt lgkmcnt(0)
	v_readfirstlane_b32 s7, v3
	v_readfirstlane_b32 s6, v2
	v_cmp_gt_i32_e32 vcc, s2, v16
	s_and_saveexec_b64 s[2:3], vcc
	s_cbranch_execz .LBB0_430
	s_add_u32 s4, s6, 0x12900000
	s_addc_u32 s5, s7, 0
	s_add_u32 s6, s6, 0x40000
	s_addc_u32 s7, s7, 0
	v_ashrrev_i32_e32 v2, 15, v16
	v_and_b32_e32 v0, 0x7fff, v16
	v_lshlrev_b32_e32 v0, 4, v0
	v_lshl_or_b32 v0, v2, 23, v0
	v_bfe_u32 v1, v16, 10, 5
	v_lshl_or_b32 v1, v2, 9, v1
	v_lshlrev_b32_e32 v1, 2, v1
	v_add_u32_e32 v2, 0x2000, v1
	v_mov_b32_e32 v3, v0
	global_load_dwordx4 v[20:23], v3, s[4:5]
	global_load_dword v80, v1, s[6:7]
	v_add_u32_e32 v95, 0x80000, v0
	global_load_dwordx4 v[24:27], v95, s[4:5]
	global_load_dword v81, v1, s[6:7] offset:128
	v_add_u32_e32 v3, 0x100000, v0
	global_load_dwordx4 v[28:31], v3, s[4:5]
	global_load_dword v82, v1, s[6:7] offset:256
	v_add_u32_e32 v95, 0x180000, v0
	global_load_dwordx4 v[32:35], v95, s[4:5]
	global_load_dword v83, v1, s[6:7] offset:384
	v_add_u32_e32 v3, 0x200000, v0
	global_load_dwordx4 v[36:39], v3, s[4:5]
	global_load_dword v84, v1, s[6:7] offset:512
	v_add_u32_e32 v95, 0x280000, v0
	global_load_dwordx4 v[40:43], v95, s[4:5]
	global_load_dword v85, v1, s[6:7] offset:640
	v_add_u32_e32 v3, 0x300000, v0
	global_load_dwordx4 v[44:47], v3, s[4:5]
	global_load_dword v86, v1, s[6:7] offset:768
	v_add_u32_e32 v95, 0x380000, v0
	global_load_dwordx4 v[48:51], v95, s[4:5]
	global_load_dword v87, v1, s[6:7] offset:896
	v_add_u32_e32 v3, 0x400000, v0
	global_load_dwordx4 v[52:55], v3, s[4:5]
	global_load_dword v88, v1, s[6:7] offset:1024
	v_add_u32_e32 v95, 0x480000, v0
	global_load_dwordx4 v[56:59], v95, s[4:5]
	global_load_dword v89, v1, s[6:7] offset:1152
	v_add_u32_e32 v3, 0x500000, v0
	global_load_dwordx4 v[60:63], v3, s[4:5]
	global_load_dword v90, v1, s[6:7] offset:1280
	v_add_u32_e32 v95, 0x580000, v0
	global_load_dwordx4 v[64:67], v95, s[4:5]
	global_load_dword v91, v1, s[6:7] offset:1408
	v_add_u32_e32 v3, 0x600000, v0
	global_load_dwordx4 v[68:71], v3, s[4:5]
	global_load_dword v92, v1, s[6:7] offset:1536
	v_add_u32_e32 v95, 0x680000, v0
	global_load_dwordx4 v[72:75], v95, s[4:5]
	global_load_dword v93, v1, s[6:7] offset:1664
	v_add_u32_e32 v3, 0x700000, v0
	global_load_dwordx4 v[76:79], v3, s[4:5]
	global_load_dword v94, v1, s[6:7] offset:1792
	v_add_u32_e32 v95, 0x2000000, v0
	global_load_dwordx4 v[96:99], v95, s[4:5]
	global_load_dword v156, v2, s[6:7]
	v_add_u32_e32 v3, 0x2080000, v0
	global_load_dwordx4 v[100:103], v3, s[4:5]
	global_load_dword v157, v2, s[6:7] offset:128
	v_add_u32_e32 v95, 0x2100000, v0
	global_load_dwordx4 v[104:107], v95, s[4:5]
	global_load_dword v158, v2, s[6:7] offset:256
	v_add_u32_e32 v3, 0x2180000, v0
	global_load_dwordx4 v[108:111], v3, s[4:5]
	global_load_dword v159, v2, s[6:7] offset:384
	v_add_u32_e32 v95, 0x2200000, v0
	global_load_dwordx4 v[112:115], v95, s[4:5]
	global_load_dword v160, v2, s[6:7] offset:512
	v_add_u32_e32 v3, 0x2280000, v0
	global_load_dwordx4 v[116:119], v3, s[4:5]
	global_load_dword v161, v2, s[6:7] offset:640
	v_add_u32_e32 v95, 0x2300000, v0
	global_load_dwordx4 v[120:123], v95, s[4:5]
	global_load_dword v162, v2, s[6:7] offset:768
	v_add_u32_e32 v3, 0x2380000, v0
	global_load_dwordx4 v[124:127], v3, s[4:5]
	global_load_dword v163, v2, s[6:7] offset:896
	v_add_u32_e32 v95, 0x2400000, v0
	global_load_dwordx4 v[128:131], v95, s[4:5]
	global_load_dword v164, v2, s[6:7] offset:1024
	v_add_u32_e32 v3, 0x2480000, v0
	global_load_dwordx4 v[132:135], v3, s[4:5]
	global_load_dword v165, v2, s[6:7] offset:1152
	v_add_u32_e32 v95, 0x2500000, v0
	global_load_dwordx4 v[136:139], v95, s[4:5]
	global_load_dword v166, v2, s[6:7] offset:1280
	v_add_u32_e32 v3, 0x2580000, v0
	global_load_dwordx4 v[140:143], v3, s[4:5]
	global_load_dword v167, v2, s[6:7] offset:1408
	v_add_u32_e32 v95, 0x2600000, v0
	global_load_dwordx4 v[144:147], v95, s[4:5]
	global_load_dword v168, v2, s[6:7] offset:1536
	v_add_u32_e32 v3, 0x2680000, v0
	global_load_dwordx4 v[148:151], v3, s[4:5]
	global_load_dword v169, v2, s[6:7] offset:1664
	v_add_u32_e32 v95, 0x2700000, v0
	global_load_dwordx4 v[152:155], v95, s[4:5]
	global_load_dword v170, v2, s[6:7] offset:1792
	v_mov_b32_e32 v4, 0
	v_mov_b32_e32 v5, 0
	v_mov_b32_e32 v6, 0
	v_mov_b32_e32 v7, 0
	v_mov_b32_e32 v8, 0
	v_mov_b32_e32 v9, 0
	v_mov_b32_e32 v10, 0
	v_mov_b32_e32 v11, 0
	v_cvt_pk_bf16_f32 v16, v4, v5
	v_cvt_pk_bf16_f32 v17, v6, v7
	v_cvt_pk_bf16_f32 v18, v8, v9
	v_cvt_pk_bf16_f32 v19, v10, v11
	v_mov_b32_e32 v3, v0
	global_store_dwordx4 v3, v[16:19], s[0:1]
	s_waitcnt vmcnt(59)
	v_lshlrev_b32_e32 v12, 16, v20
	v_and_b32_e32 v20, 0xffff0000, v20
	v_lshlrev_b32_e32 v13, 16, v21
	v_and_b32_e32 v21, 0xffff0000, v21
	v_lshlrev_b32_e32 v14, 16, v22
	v_and_b32_e32 v22, 0xffff0000, v22
	v_lshlrev_b32_e32 v15, 16, v23
	v_and_b32_e32 v23, 0xffff0000, v23
	v_fma_f32 v4, v80, v4, v12
	v_fma_f32 v5, v80, v5, v20
	v_fma_f32 v6, v80, v6, v13
	v_fma_f32 v7, v80, v7, v21
	v_fma_f32 v8, v80, v8, v14
	v_fma_f32 v9, v80, v9, v22
	v_fma_f32 v10, v80, v10, v15
	v_fma_f32 v11, v80, v11, v23
	v_cvt_pk_bf16_f32 v172, v4, v5
	v_cvt_pk_bf16_f32 v173, v6, v7
	v_cvt_pk_bf16_f32 v174, v8, v9
	v_cvt_pk_bf16_f32 v175, v10, v11
	v_add_u32_e32 v95, 0x80000, v0
	global_store_dwordx4 v95, v[172:175], s[0:1]
	s_waitcnt vmcnt(58)
; __device__ __forceinline__ void unpack8(u32x4 r, float* f) { f[0] = bflo(r.x); f[1] = bfhi(r.x); f[2] = bflo(r.y); f[3] = bfhi(r.y); f[4] = bflo(r.z); f[5] = bfhi(r.z); f[6] = bflo(r.w); f[7] = bfhi(r.w); }
; __device__ __forceinline__ u32x4 pack8(const float* f) { u32x4 o; o.x = pk2(f[0], f[1]); o.y = pk2(f[2], f[3]); o.z = pk2(f[4], f[5]); o.w = pk2(f[6], f[7]); return o; }
; __device__ __forceinline__ void phase_scan(const PT& p, int tid) {
;     ...
; #pragma unroll
;         for (int c = 0; c < 16; ++c) {
;             const size_t off = ((size_t)(b * 16 + c) * 32 * 64 * 16 + rem) * 8;
;             *(u32x4*)(PV + off) = pack8(run);
;             if (c < 15) { float s[8]; unpack8(*(const u32x4*)(ST + off), s); const float cd = CD[(b * 16 + c) * 32 + hh];
; #pragma unroll
;                 for (int j = 0; j < 8; ++j) run[j] = run[j] * cd + s[j]; }
;         }
	v_lshlrev_b32_e32 v12, 16, v24
	v_and_b32_e32 v24, 0xffff0000, v24
	v_lshlrev_b32_e32 v13, 16, v25
	v_and_b32_e32 v25, 0xffff0000, v25
	v_lshlrev_b32_e32 v14, 16, v26
	v_and_b32_e32 v26, 0xffff0000, v26
	v_lshlrev_b32_e32 v15, 16, v27
	v_and_b32_e32 v27, 0xffff0000, v27
	v_fma_f32 v4, v81, v4, v12
	v_fma_f32 v5, v81, v5, v24
	v_fma_f32 v6, v81, v6, v13
	v_fma_f32 v7, v81, v7, v25
	v_fma_f32 v8, v81, v8, v14
	v_fma_f32 v9, v81, v9, v26
	v_fma_f32 v10, v81, v10, v15
	v_fma_f32 v11, v81, v11, v27
	v_cvt_pk_bf16_f32 v16, v4, v5
	v_cvt_pk_bf16_f32 v17, v6, v7
	v_cvt_pk_bf16_f32 v18, v8, v9
	v_cvt_pk_bf16_f32 v19, v10, v11
	v_add_u32_e32 v3, 0x100000, v0
	global_store_dwordx4 v3, v[16:19], s[0:1]
	s_waitcnt vmcnt(57)
	v_lshlrev_b32_e32 v12, 16, v28
	v_and_b32_e32 v28, 0xffff0000, v28
	v_lshlrev_b32_e32 v13, 16, v29
	v_and_b32_e32 v29, 0xffff0000, v29
	v_lshlrev_b32_e32 v14, 16, v30
	v_and_b32_e32 v30, 0xffff0000, v30
	v_lshlrev_b32_e32 v15, 16, v31
	v_and_b32_e32 v31, 0xffff0000, v31
	v_fma_f32 v4, v82, v4, v12
	v_fma_f32 v5, v82, v5, v28
	v_fma_f32 v6, v82, v6, v13
	v_fma_f32 v7, v82, v7, v29
	v_fma_f32 v8, v82, v8, v14
	v_fma_f32 v9, v82, v9, v30
	v_fma_f32 v10, v82, v10, v15
	v_fma_f32 v11, v82, v11, v31
	v_cvt_pk_bf16_f32 v172, v4, v5
	v_cvt_pk_bf16_f32 v173, v6, v7
	v_cvt_pk_bf16_f32 v174, v8, v9
	v_cvt_pk_bf16_f32 v175, v10, v11
	v_add_u32_e32 v95, 0x180000, v0
	global_store_dwordx4 v95, v[172:175], s[0:1]
	s_waitcnt vmcnt(56)
	v_lshlrev_b32_e32 v12, 16, v32
	v_and_b32_e32 v32, 0xffff0000, v32
	v_lshlrev_b32_e32 v13, 16, v33
	v_and_b32_e32 v33, 0xffff0000, v33
	v_lshlrev_b32_e32 v14, 16, v34
	v_and_b32_e32 v34, 0xffff0000, v34
	v_lshlrev_b32_e32 v15, 16, v35
	v_and_b32_e32 v35, 0xffff0000, v35
	v_fma_f32 v4, v83, v4, v12
	v_fma_f32 v5, v83, v5, v32
	v_fma_f32 v6, v83, v6, v13
	v_fma_f32 v7, v83, v7, v33
	v_fma_f32 v8, v83, v8, v14
	v_fma_f32 v9, v83, v9, v34
	v_fma_f32 v10, v83, v10, v15
	v_fma_f32 v11, v83, v11, v35
	v_cvt_pk_bf16_f32 v16, v4, v5
	v_cvt_pk_bf16_f32 v17, v6, v7
	v_cvt_pk_bf16_f32 v18, v8, v9
	v_cvt_pk_bf16_f32 v19, v10, v11
	v_add_u32_e32 v3, 0x200000, v0
	global_store_dwordx4 v3, v[16:19], s[0:1]
	s_waitcnt vmcnt(55)
	v_lshlrev_b32_e32 v12, 16, v36
	v_and_b32_e32 v36, 0xffff0000, v36
	v_lshlrev_b32_e32 v13, 16, v37
	v_and_b32_e32 v37, 0xffff0000, v37
	v_lshlrev_b32_e32 v14, 16, v38
	v_and_b32_e32 v38, 0xffff0000, v38
	v_lshlrev_b32_e32 v15, 16, v39
	v_and_b32_e32 v39, 0xffff0000, v39
	v_fma_f32 v4, v84, v4, v12
	v_fma_f32 v5, v84, v5, v36
	v_fma_f32 v6, v84, v6, v13
	v_fma_f32 v7, v84, v7, v37
	v_fma_f32 v8, v84, v8, v14
	v_fma_f32 v9, v84, v9, v38
	v_fma_f32 v10, v84, v10, v15
	v_fma_f32 v11, v84, v11, v39
	v_cvt_pk_bf16_f32 v172, v4, v5
	v_cvt_pk_bf16_f32 v173, v6, v7
	v_cvt_pk_bf16_f32 v174, v8, v9
	v_cvt_pk_bf16_f32 v175, v10, v11
	v_add_u32_e32 v95, 0x280000, v0
	global_store_dwordx4 v95, v[172:175], s[0:1]
	s_waitcnt vmcnt(54)
	v_lshlrev_b32_e32 v12, 16, v40
	v_and_b32_e32 v40, 0xffff0000, v40
	v_lshlrev_b32_e32 v13, 16, v41
	v_and_b32_e32 v41, 0xffff0000, v41
	v_lshlrev_b32_e32 v14, 16, v42
	v_and_b32_e32 v42, 0xffff0000, v42
	v_lshlrev_b32_e32 v15, 16, v43
	v_and_b32_e32 v43, 0xffff0000, v43
	v_fma_f32 v4, v85, v4, v12
	v_fma_f32 v5, v85, v5, v40
	v_fma_f32 v6, v85, v6, v13
	v_fma_f32 v7, v85, v7, v41
	v_fma_f32 v8, v85, v8, v14
	v_fma_f32 v9, v85, v9, v42
	v_fma_f32 v10, v85, v10, v15
	v_fma_f32 v11, v85, v11, v43
	v_cvt_pk_bf16_f32 v16, v4, v5
	v_cvt_pk_bf16_f32 v17, v6, v7
	v_cvt_pk_bf16_f32 v18, v8, v9
	v_cvt_pk_bf16_f32 v19, v10, v11
	v_add_u32_e32 v3, 0x300000, v0
	global_store_dwordx4 v3, v[16:19], s[0:1]
	s_waitcnt vmcnt(53)
	v_lshlrev_b32_e32 v12, 16, v44
	v_and_b32_e32 v44, 0xffff0000, v44
	v_lshlrev_b32_e32 v13, 16, v45
	v_and_b32_e32 v45, 0xffff0000, v45
	v_lshlrev_b32_e32 v14, 16, v46
	v_and_b32_e32 v46, 0xffff0000, v46
	v_lshlrev_b32_e32 v15, 16, v47
	v_and_b32_e32 v47, 0xffff0000, v47
	v_fma_f32 v4, v86, v4, v12
	v_fma_f32 v5, v86, v5, v44
	v_fma_f32 v6, v86, v6, v13
	v_fma_f32 v7, v86, v7, v45
	v_fma_f32 v8, v86, v8, v14
	v_fma_f32 v9, v86, v9, v46
	v_fma_f32 v10, v86, v10, v15
	v_fma_f32 v11, v86, v11, v47
	v_cvt_pk_bf16_f32 v172, v4, v5
	v_cvt_pk_bf16_f32 v173, v6, v7
	v_cvt_pk_bf16_f32 v174, v8, v9
	v_cvt_pk_bf16_f32 v175, v10, v11
	v_add_u32_e32 v95, 0x380000, v0
	global_store_dwordx4 v95, v[172:175], s[0:1]
	s_waitcnt vmcnt(52)
	v_lshlrev_b32_e32 v12, 16, v48
	v_and_b32_e32 v48, 0xffff0000, v48
	v_lshlrev_b32_e32 v13, 16, v49
	v_and_b32_e32 v49, 0xffff0000, v49
	v_lshlrev_b32_e32 v14, 16, v50
	v_and_b32_e32 v50, 0xffff0000, v50
	v_lshlrev_b32_e32 v15, 16, v51
	v_and_b32_e32 v51, 0xffff0000, v51
	v_fma_f32 v4, v87, v4, v12
	v_fma_f32 v5, v87, v5, v48
	v_fma_f32 v6, v87, v6, v13
	v_fma_f32 v7, v87, v7, v49
	v_fma_f32 v8, v87, v8, v14
	v_fma_f32 v9, v87, v9, v50
	v_fma_f32 v10, v87, v10, v15
	v_fma_f32 v11, v87, v11, v51
	v_cvt_pk_bf16_f32 v16, v4, v5
	v_cvt_pk_bf16_f32 v17, v6, v7
	v_cvt_pk_bf16_f32 v18, v8, v9
	v_cvt_pk_bf16_f32 v19, v10, v11
	v_add_u32_e32 v3, 0x400000, v0
	global_store_dwordx4 v3, v[16:19], s[0:1]
	s_waitcnt vmcnt(51)
	v_lshlrev_b32_e32 v12, 16, v52
	v_and_b32_e32 v52, 0xffff0000, v52
	v_lshlrev_b32_e32 v13, 16, v53
	v_and_b32_e32 v53, 0xffff0000, v53
	v_lshlrev_b32_e32 v14, 16, v54
	v_and_b32_e32 v54, 0xffff0000, v54
	v_lshlrev_b32_e32 v15, 16, v55
	v_and_b32_e32 v55, 0xffff0000, v55
	v_fma_f32 v4, v88, v4, v12
	v_fma_f32 v5, v88, v5, v52
	v_fma_f32 v6, v88, v6, v13
	v_fma_f32 v7, v88, v7, v53
	v_fma_f32 v8, v88, v8, v14
	v_fma_f32 v9, v88, v9, v54
	v_fma_f32 v10, v88, v10, v15
	v_fma_f32 v11, v88, v11, v55
	v_cvt_pk_bf16_f32 v172, v4, v5
	v_cvt_pk_bf16_f32 v173, v6, v7
	v_cvt_pk_bf16_f32 v174, v8, v9
	v_cvt_pk_bf16_f32 v175, v10, v11
	v_add_u32_e32 v95, 0x480000, v0
	global_store_dwordx4 v95, v[172:175], s[0:1]
	s_waitcnt vmcnt(50)
; __device__ __forceinline__ void unpack8(u32x4 r, float* f) { f[0] = bflo(r.x); f[1] = bfhi(r.x); f[2] = bflo(r.y); f[3] = bfhi(r.y); f[4] = bflo(r.z); f[5] = bfhi(r.z); f[6] = bflo(r.w); f[7] = bfhi(r.w); }
; __device__ __forceinline__ u32x4 pack8(const float* f) { u32x4 o; o.x = pk2(f[0], f[1]); o.y = pk2(f[2], f[3]); o.z = pk2(f[4], f[5]); o.w = pk2(f[6], f[7]); return o; }
; __device__ __forceinline__ void phase_scan(const PT& p, int tid) {
;     ...
; #pragma unroll
;         for (int c = 0; c < 16; ++c) {
;             const size_t off = ((size_t)(b * 16 + c) * 32 * 64 * 16 + rem) * 8;
;             *(u32x4*)(PV + off) = pack8(run);
;             if (c < 15) { float s[8]; unpack8(*(const u32x4*)(ST + off), s); const float cd = CD[(b * 16 + c) * 32 + hh];
; #pragma unroll
;                 for (int j = 0; j < 8; ++j) run[j] = run[j] * cd + s[j]; }
;         }
	v_lshlrev_b32_e32 v12, 16, v56
	v_and_b32_e32 v56, 0xffff0000, v56
	v_lshlrev_b32_e32 v13, 16, v57
	v_and_b32_e32 v57, 0xffff0000, v57
	v_lshlrev_b32_e32 v14, 16, v58
	v_and_b32_e32 v58, 0xffff0000, v58
	v_lshlrev_b32_e32 v15, 16, v59
	v_and_b32_e32 v59, 0xffff0000, v59
	v_fma_f32 v4, v89, v4, v12
	v_fma_f32 v5, v89, v5, v56
	v_fma_f32 v6, v89, v6, v13
	v_fma_f32 v7, v89, v7, v57
	v_fma_f32 v8, v89, v8, v14
	v_fma_f32 v9, v89, v9, v58
	v_fma_f32 v10, v89, v10, v15
	v_fma_f32 v11, v89, v11, v59
	v_cvt_pk_bf16_f32 v16, v4, v5
	v_cvt_pk_bf16_f32 v17, v6, v7
	v_cvt_pk_bf16_f32 v18, v8, v9
	v_cvt_pk_bf16_f32 v19, v10, v11
	v_add_u32_e32 v3, 0x500000, v0
	global_store_dwordx4 v3, v[16:19], s[0:1]
	s_waitcnt vmcnt(49)
	v_lshlrev_b32_e32 v12, 16, v60
	v_and_b32_e32 v60, 0xffff0000, v60
	v_lshlrev_b32_e32 v13, 16, v61
	v_and_b32_e32 v61, 0xffff0000, v61
	v_lshlrev_b32_e32 v14, 16, v62
	v_and_b32_e32 v62, 0xffff0000, v62
	v_lshlrev_b32_e32 v15, 16, v63
	v_and_b32_e32 v63, 0xffff0000, v63
	v_fma_f32 v4, v90, v4, v12
	v_fma_f32 v5, v90, v5, v60
	v_fma_f32 v6, v90, v6, v13
	v_fma_f32 v7, v90, v7, v61
	v_fma_f32 v8, v90, v8, v14
	v_fma_f32 v9, v90, v9, v62
	v_fma_f32 v10, v90, v10, v15
	v_fma_f32 v11, v90, v11, v63
	v_cvt_pk_bf16_f32 v172, v4, v5
	v_cvt_pk_bf16_f32 v173, v6, v7
	v_cvt_pk_bf16_f32 v174, v8, v9
	v_cvt_pk_bf16_f32 v175, v10, v11
	v_add_u32_e32 v95, 0x580000, v0
	global_store_dwordx4 v95, v[172:175], s[0:1]
	s_waitcnt vmcnt(48)
	v_lshlrev_b32_e32 v12, 16, v64
	v_and_b32_e32 v64, 0xffff0000, v64
	v_lshlrev_b32_e32 v13, 16, v65
	v_and_b32_e32 v65, 0xffff0000, v65
	v_lshlrev_b32_e32 v14, 16, v66
	v_and_b32_e32 v66, 0xffff0000, v66
	v_lshlrev_b32_e32 v15, 16, v67
	v_and_b32_e32 v67, 0xffff0000, v67
	v_fma_f32 v4, v91, v4, v12
	v_fma_f32 v5, v91, v5, v64
	v_fma_f32 v6, v91, v6, v13
	v_fma_f32 v7, v91, v7, v65
	v_fma_f32 v8, v91, v8, v14
	v_fma_f32 v9, v91, v9, v66
	v_fma_f32 v10, v91, v10, v15
	v_fma_f32 v11, v91, v11, v67
	v_cvt_pk_bf16_f32 v16, v4, v5
	v_cvt_pk_bf16_f32 v17, v6, v7
	v_cvt_pk_bf16_f32 v18, v8, v9
	v_cvt_pk_bf16_f32 v19, v10, v11
	v_add_u32_e32 v3, 0x600000, v0
	global_store_dwordx4 v3, v[16:19], s[0:1]
	s_waitcnt vmcnt(47)
	v_lshlrev_b32_e32 v12, 16, v68
	v_and_b32_e32 v68, 0xffff0000, v68
	v_lshlrev_b32_e32 v13, 16, v69
	v_and_b32_e32 v69, 0xffff0000, v69
	v_lshlrev_b32_e32 v14, 16, v70
	v_and_b32_e32 v70, 0xffff0000, v70
	v_lshlrev_b32_e32 v15, 16, v71
	v_and_b32_e32 v71, 0xffff0000, v71
	v_fma_f32 v4, v92, v4, v12
	v_fma_f32 v5, v92, v5, v68
	v_fma_f32 v6, v92, v6, v13
	v_fma_f32 v7, v92, v7, v69
	v_fma_f32 v8, v92, v8, v14
	v_fma_f32 v9, v92, v9, v70
	v_fma_f32 v10, v92, v10, v15
	v_fma_f32 v11, v92, v11, v71
	v_cvt_pk_bf16_f32 v172, v4, v5
	v_cvt_pk_bf16_f32 v173, v6, v7
	v_cvt_pk_bf16_f32 v174, v8, v9
	v_cvt_pk_bf16_f32 v175, v10, v11
	v_add_u32_e32 v95, 0x680000, v0
	global_store_dwordx4 v95, v[172:175], s[0:1]
	s_waitcnt vmcnt(46)
	v_lshlrev_b32_e32 v12, 16, v72
	v_and_b32_e32 v72, 0xffff0000, v72
	v_lshlrev_b32_e32 v13, 16, v73
	v_and_b32_e32 v73, 0xffff0000, v73
	v_lshlrev_b32_e32 v14, 16, v74
	v_and_b32_e32 v74, 0xffff0000, v74
	v_lshlrev_b32_e32 v15, 16, v75
	v_and_b32_e32 v75, 0xffff0000, v75
	v_fma_f32 v4, v93, v4, v12
	v_fma_f32 v5, v93, v5, v72
	v_fma_f32 v6, v93, v6, v13
	v_fma_f32 v7, v93, v7, v73
	v_fma_f32 v8, v93, v8, v14
	v_fma_f32 v9, v93, v9, v74
	v_fma_f32 v10, v93, v10, v15
	v_fma_f32 v11, v93, v11, v75
	v_cvt_pk_bf16_f32 v16, v4, v5
	v_cvt_pk_bf16_f32 v17, v6, v7
	v_cvt_pk_bf16_f32 v18, v8, v9
	v_cvt_pk_bf16_f32 v19, v10, v11
	v_add_u32_e32 v3, 0x700000, v0
	global_store_dwordx4 v3, v[16:19], s[0:1]
	s_waitcnt vmcnt(45)
	v_lshlrev_b32_e32 v12, 16, v76
	v_and_b32_e32 v76, 0xffff0000, v76
	v_lshlrev_b32_e32 v13, 16, v77
	v_and_b32_e32 v77, 0xffff0000, v77
	v_lshlrev_b32_e32 v14, 16, v78
	v_and_b32_e32 v78, 0xffff0000, v78
	v_lshlrev_b32_e32 v15, 16, v79
	v_and_b32_e32 v79, 0xffff0000, v79
	v_fma_f32 v4, v94, v4, v12
	v_fma_f32 v5, v94, v5, v76
	v_fma_f32 v6, v94, v6, v13
	v_fma_f32 v7, v94, v7, v77
	v_fma_f32 v8, v94, v8, v14
	v_fma_f32 v9, v94, v9, v78
	v_fma_f32 v10, v94, v10, v15
	v_fma_f32 v11, v94, v11, v79
	v_cvt_pk_bf16_f32 v172, v4, v5
	v_cvt_pk_bf16_f32 v173, v6, v7
	v_cvt_pk_bf16_f32 v174, v8, v9
	v_cvt_pk_bf16_f32 v175, v10, v11
	v_add_u32_e32 v95, 0x780000, v0
	global_store_dwordx4 v95, v[172:175], s[0:1]
	v_mov_b32_e32 v4, 0
	v_mov_b32_e32 v5, 0
	v_mov_b32_e32 v6, 0
	v_mov_b32_e32 v7, 0
	v_mov_b32_e32 v8, 0
	v_mov_b32_e32 v9, 0
	v_mov_b32_e32 v10, 0
	v_mov_b32_e32 v11, 0
	v_cvt_pk_bf16_f32 v16, v4, v5
	v_cvt_pk_bf16_f32 v17, v6, v7
	v_cvt_pk_bf16_f32 v18, v8, v9
	v_cvt_pk_bf16_f32 v19, v10, v11
	v_add_u32_e32 v3, 0x2000000, v0
	global_store_dwordx4 v3, v[16:19], s[0:1]
	s_waitcnt vmcnt(45)
	v_lshlrev_b32_e32 v12, 16, v96
	v_and_b32_e32 v96, 0xffff0000, v96
	v_lshlrev_b32_e32 v13, 16, v97
	v_and_b32_e32 v97, 0xffff0000, v97
	v_lshlrev_b32_e32 v14, 16, v98
	v_and_b32_e32 v98, 0xffff0000, v98
	v_lshlrev_b32_e32 v15, 16, v99
	v_and_b32_e32 v99, 0xffff0000, v99
	v_fma_f32 v4, v156, v4, v12
	v_fma_f32 v5, v156, v5, v96
	v_fma_f32 v6, v156, v6, v13
	v_fma_f32 v7, v156, v7, v97
	v_fma_f32 v8, v156, v8, v14
	v_fma_f32 v9, v156, v9, v98
	v_fma_f32 v10, v156, v10, v15
	v_fma_f32 v11, v156, v11, v99
	v_cvt_pk_bf16_f32 v172, v4, v5
	v_cvt_pk_bf16_f32 v173, v6, v7
	v_cvt_pk_bf16_f32 v174, v8, v9
	v_cvt_pk_bf16_f32 v175, v10, v11
	v_add_u32_e32 v95, 0x2080000, v0
	global_store_dwordx4 v95, v[172:175], s[0:1]
	s_waitcnt vmcnt(44)
; __device__ __forceinline__ void unpack8(u32x4 r, float* f) { f[0] = bflo(r.x); f[1] = bfhi(r.x); f[2] = bflo(r.y); f[3] = bfhi(r.y); f[4] = bflo(r.z); f[5] = bfhi(r.z); f[6] = bflo(r.w); f[7] = bfhi(r.w); }
; __device__ __forceinline__ u32x4 pack8(const float* f) { u32x4 o; o.x = pk2(f[0], f[1]); o.y = pk2(f[2], f[3]); o.z = pk2(f[4], f[5]); o.w = pk2(f[6], f[7]); return o; }
; __device__ __forceinline__ void phase_scan(const PT& p, int tid) {
;     ...
; #pragma unroll
;         for (int c = 0; c < 16; ++c) {
;             const size_t off = ((size_t)(b * 16 + c) * 32 * 64 * 16 + rem) * 8;
;             *(u32x4*)(PV + off) = pack8(run);
;             if (c < 15) { float s[8]; unpack8(*(const u32x4*)(ST + off), s); const float cd = CD[(b * 16 + c) * 32 + hh];
; #pragma unroll
;                 for (int j = 0; j < 8; ++j) run[j] = run[j] * cd + s[j]; }
;         }
	v_lshlrev_b32_e32 v12, 16, v100
	v_and_b32_e32 v100, 0xffff0000, v100
	v_lshlrev_b32_e32 v13, 16, v101
	v_and_b32_e32 v101, 0xffff0000, v101
	v_lshlrev_b32_e32 v14, 16, v102
	v_and_b32_e32 v102, 0xffff0000, v102
	v_lshlrev_b32_e32 v15, 16, v103
	v_and_b32_e32 v103, 0xffff0000, v103
	v_fma_f32 v4, v157, v4, v12
	v_fma_f32 v5, v157, v5, v100
	v_fma_f32 v6, v157, v6, v13
	v_fma_f32 v7, v157, v7, v101
	v_fma_f32 v8, v157, v8, v14
	v_fma_f32 v9, v157, v9, v102
	v_fma_f32 v10, v157, v10, v15
	v_fma_f32 v11, v157, v11, v103
	v_cvt_pk_bf16_f32 v16, v4, v5
	v_cvt_pk_bf16_f32 v17, v6, v7
	v_cvt_pk_bf16_f32 v18, v8, v9
	v_cvt_pk_bf16_f32 v19, v10, v11
	v_add_u32_e32 v3, 0x2100000, v0
	global_store_dwordx4 v3, v[16:19], s[0:1]
	s_waitcnt vmcnt(43)
	v_lshlrev_b32_e32 v12, 16, v104
	v_and_b32_e32 v104, 0xffff0000, v104
	v_lshlrev_b32_e32 v13, 16, v105
	v_and_b32_e32 v105, 0xffff0000, v105
	v_lshlrev_b32_e32 v14, 16, v106
	v_and_b32_e32 v106, 0xffff0000, v106
	v_lshlrev_b32_e32 v15, 16, v107
	v_and_b32_e32 v107, 0xffff0000, v107
	v_fma_f32 v4, v158, v4, v12
	v_fma_f32 v5, v158, v5, v104
	v_fma_f32 v6, v158, v6, v13
	v_fma_f32 v7, v158, v7, v105
	v_fma_f32 v8, v158, v8, v14
	v_fma_f32 v9, v158, v9, v106
	v_fma_f32 v10, v158, v10, v15
	v_fma_f32 v11, v158, v11, v107
	v_cvt_pk_bf16_f32 v172, v4, v5
	v_cvt_pk_bf16_f32 v173, v6, v7
	v_cvt_pk_bf16_f32 v174, v8, v9
	v_cvt_pk_bf16_f32 v175, v10, v11
	v_add_u32_e32 v95, 0x2180000, v0
	global_store_dwordx4 v95, v[172:175], s[0:1]
	s_waitcnt vmcnt(42)
	v_lshlrev_b32_e32 v12, 16, v108
	v_and_b32_e32 v108, 0xffff0000, v108
	v_lshlrev_b32_e32 v13, 16, v109
	v_and_b32_e32 v109, 0xffff0000, v109
	v_lshlrev_b32_e32 v14, 16, v110
	v_and_b32_e32 v110, 0xffff0000, v110
	v_lshlrev_b32_e32 v15, 16, v111
	v_and_b32_e32 v111, 0xffff0000, v111
	v_fma_f32 v4, v159, v4, v12
	v_fma_f32 v5, v159, v5, v108
	v_fma_f32 v6, v159, v6, v13
	v_fma_f32 v7, v159, v7, v109
	v_fma_f32 v8, v159, v8, v14
	v_fma_f32 v9, v159, v9, v110
	v_fma_f32 v10, v159, v10, v15
	v_fma_f32 v11, v159, v11, v111
	v_cvt_pk_bf16_f32 v16, v4, v5
	v_cvt_pk_bf16_f32 v17, v6, v7
	v_cvt_pk_bf16_f32 v18, v8, v9
	v_cvt_pk_bf16_f32 v19, v10, v11
	v_add_u32_e32 v3, 0x2200000, v0
	global_store_dwordx4 v3, v[16:19], s[0:1]
	s_waitcnt vmcnt(41)
	v_lshlrev_b32_e32 v12, 16, v112
	v_and_b32_e32 v112, 0xffff0000, v112
	v_lshlrev_b32_e32 v13, 16, v113
	v_and_b32_e32 v113, 0xffff0000, v113
	v_lshlrev_b32_e32 v14, 16, v114
	v_and_b32_e32 v114, 0xffff0000, v114
	v_lshlrev_b32_e32 v15, 16, v115
	v_and_b32_e32 v115, 0xffff0000, v115
	v_fma_f32 v4, v160, v4, v12
	v_fma_f32 v5, v160, v5, v112
	v_fma_f32 v6, v160, v6, v13
	v_fma_f32 v7, v160, v7, v113
	v_fma_f32 v8, v160, v8, v14
	v_fma_f32 v9, v160, v9, v114
	v_fma_f32 v10, v160, v10, v15
	v_fma_f32 v11, v160, v11, v115
	v_cvt_pk_bf16_f32 v172, v4, v5
	v_cvt_pk_bf16_f32 v173, v6, v7
	v_cvt_pk_bf16_f32 v174, v8, v9
	v_cvt_pk_bf16_f32 v175, v10, v11
	v_add_u32_e32 v95, 0x2280000, v0
	global_store_dwordx4 v95, v[172:175], s[0:1]
	s_waitcnt vmcnt(40)
	v_lshlrev_b32_e32 v12, 16, v116
	v_and_b32_e32 v116, 0xffff0000, v116
	v_lshlrev_b32_e32 v13, 16, v117
	v_and_b32_e32 v117, 0xffff0000, v117
	v_lshlrev_b32_e32 v14, 16, v118
	v_and_b32_e32 v118, 0xffff0000, v118
	v_lshlrev_b32_e32 v15, 16, v119
	v_and_b32_e32 v119, 0xffff0000, v119
	v_fma_f32 v4, v161, v4, v12
	v_fma_f32 v5, v161, v5, v116
	v_fma_f32 v6, v161, v6, v13
	v_fma_f32 v7, v161, v7, v117
	v_fma_f32 v8, v161, v8, v14
	v_fma_f32 v9, v161, v9, v118
	v_fma_f32 v10, v161, v10, v15
	v_fma_f32 v11, v161, v11, v119
	v_cvt_pk_bf16_f32 v16, v4, v5
	v_cvt_pk_bf16_f32 v17, v6, v7
	v_cvt_pk_bf16_f32 v18, v8, v9
	v_cvt_pk_bf16_f32 v19, v10, v11
	v_add_u32_e32 v3, 0x2300000, v0
	global_store_dwordx4 v3, v[16:19], s[0:1]
	s_waitcnt vmcnt(39)
	v_lshlrev_b32_e32 v12, 16, v120
	v_and_b32_e32 v120, 0xffff0000, v120
	v_lshlrev_b32_e32 v13, 16, v121
	v_and_b32_e32 v121, 0xffff0000, v121
	v_lshlrev_b32_e32 v14, 16, v122
	v_and_b32_e32 v122, 0xffff0000, v122
	v_lshlrev_b32_e32 v15, 16, v123
	v_and_b32_e32 v123, 0xffff0000, v123
	v_fma_f32 v4, v162, v4, v12
	v_fma_f32 v5, v162, v5, v120
	v_fma_f32 v6, v162, v6, v13
	v_fma_f32 v7, v162, v7, v121
	v_fma_f32 v8, v162, v8, v14
	v_fma_f32 v9, v162, v9, v122
	v_fma_f32 v10, v162, v10, v15
	v_fma_f32 v11, v162, v11, v123
	v_cvt_pk_bf16_f32 v172, v4, v5
	v_cvt_pk_bf16_f32 v173, v6, v7
	v_cvt_pk_bf16_f32 v174, v8, v9
	v_cvt_pk_bf16_f32 v175, v10, v11
	v_add_u32_e32 v95, 0x2380000, v0
	global_store_dwordx4 v95, v[172:175], s[0:1]
	s_waitcnt vmcnt(38)
	v_lshlrev_b32_e32 v12, 16, v124
	v_and_b32_e32 v124, 0xffff0000, v124
	v_lshlrev_b32_e32 v13, 16, v125
	v_and_b32_e32 v125, 0xffff0000, v125
	v_lshlrev_b32_e32 v14, 16, v126
	v_and_b32_e32 v126, 0xffff0000, v126
	v_lshlrev_b32_e32 v15, 16, v127
	v_and_b32_e32 v127, 0xffff0000, v127
	v_fma_f32 v4, v163, v4, v12
	v_fma_f32 v5, v163, v5, v124
	v_fma_f32 v6, v163, v6, v13
	v_fma_f32 v7, v163, v7, v125
	v_fma_f32 v8, v163, v8, v14
	v_fma_f32 v9, v163, v9, v126
	v_fma_f32 v10, v163, v10, v15
	v_fma_f32 v11, v163, v11, v127
	v_cvt_pk_bf16_f32 v16, v4, v5
	v_cvt_pk_bf16_f32 v17, v6, v7
	v_cvt_pk_bf16_f32 v18, v8, v9
	v_cvt_pk_bf16_f32 v19, v10, v11
	v_add_u32_e32 v3, 0x2400000, v0
	global_store_dwordx4 v3, v[16:19], s[0:1]
	s_waitcnt vmcnt(37)
; __device__ __forceinline__ void unpack8(u32x4 r, float* f) { f[0] = bflo(r.x); f[1] = bfhi(r.x); f[2] = bflo(r.y); f[3] = bfhi(r.y); f[4] = bflo(r.z); f[5] = bfhi(r.z); f[6] = bflo(r.w); f[7] = bfhi(r.w); }
; __device__ __forceinline__ u32x4 pack8(const float* f) { u32x4 o; o.x = pk2(f[0], f[1]); o.y = pk2(f[2], f[3]); o.z = pk2(f[4], f[5]); o.w = pk2(f[6], f[7]); return o; }
; __device__ __forceinline__ void phase_scan(const PT& p, int tid) {
;     ...
; #pragma unroll
;         for (int c = 0; c < 16; ++c) {
;             const size_t off = ((size_t)(b * 16 + c) * 32 * 64 * 16 + rem) * 8;
;             *(u32x4*)(PV + off) = pack8(run);
;             if (c < 15) { float s[8]; unpack8(*(const u32x4*)(ST + off), s); const float cd = CD[(b * 16 + c) * 32 + hh];
; #pragma unroll
;                 for (int j = 0; j < 8; ++j) run[j] = run[j] * cd + s[j]; }
;         }
	v_lshlrev_b32_e32 v12, 16, v128
	v_and_b32_e32 v128, 0xffff0000, v128
	v_lshlrev_b32_e32 v13, 16, v129
	v_and_b32_e32 v129, 0xffff0000, v129
	v_lshlrev_b32_e32 v14, 16, v130
	v_and_b32_e32 v130, 0xffff0000, v130
	v_lshlrev_b32_e32 v15, 16, v131
	v_and_b32_e32 v131, 0xffff0000, v131
	v_fma_f32 v4, v164, v4, v12
	v_fma_f32 v5, v164, v5, v128
	v_fma_f32 v6, v164, v6, v13
	v_fma_f32 v7, v164, v7, v129
	v_fma_f32 v8, v164, v8, v14
	v_fma_f32 v9, v164, v9, v130
	v_fma_f32 v10, v164, v10, v15
	v_fma_f32 v11, v164, v11, v131
	v_cvt_pk_bf16_f32 v172, v4, v5
	v_cvt_pk_bf16_f32 v173, v6, v7
	v_cvt_pk_bf16_f32 v174, v8, v9
	v_cvt_pk_bf16_f32 v175, v10, v11
	v_add_u32_e32 v95, 0x2480000, v0
	global_store_dwordx4 v95, v[172:175], s[0:1]
	s_waitcnt vmcnt(36)
	v_lshlrev_b32_e32 v12, 16, v132
	v_and_b32_e32 v132, 0xffff0000, v132
	v_lshlrev_b32_e32 v13, 16, v133
	v_and_b32_e32 v133, 0xffff0000, v133
	v_lshlrev_b32_e32 v14, 16, v134
	v_and_b32_e32 v134, 0xffff0000, v134
	v_lshlrev_b32_e32 v15, 16, v135
	v_and_b32_e32 v135, 0xffff0000, v135
	v_fma_f32 v4, v165, v4, v12
	v_fma_f32 v5, v165, v5, v132
	v_fma_f32 v6, v165, v6, v13
	v_fma_f32 v7, v165, v7, v133
	v_fma_f32 v8, v165, v8, v14
	v_fma_f32 v9, v165, v9, v134
	v_fma_f32 v10, v165, v10, v15
	v_fma_f32 v11, v165, v11, v135
	v_cvt_pk_bf16_f32 v16, v4, v5
	v_cvt_pk_bf16_f32 v17, v6, v7
	v_cvt_pk_bf16_f32 v18, v8, v9
	v_cvt_pk_bf16_f32 v19, v10, v11
	v_add_u32_e32 v3, 0x2500000, v0
	global_store_dwordx4 v3, v[16:19], s[0:1]
	s_waitcnt vmcnt(35)
	v_lshlrev_b32_e32 v12, 16, v136
	v_and_b32_e32 v136, 0xffff0000, v136
	v_lshlrev_b32_e32 v13, 16, v137
	v_and_b32_e32 v137, 0xffff0000, v137
	v_lshlrev_b32_e32 v14, 16, v138
	v_and_b32_e32 v138, 0xffff0000, v138
	v_lshlrev_b32_e32 v15, 16, v139
	v_and_b32_e32 v139, 0xffff0000, v139
	v_fma_f32 v4, v166, v4, v12
	v_fma_f32 v5, v166, v5, v136
	v_fma_f32 v6, v166, v6, v13
	v_fma_f32 v7, v166, v7, v137
	v_fma_f32 v8, v166, v8, v14
	v_fma_f32 v9, v166, v9, v138
	v_fma_f32 v10, v166, v10, v15
	v_fma_f32 v11, v166, v11, v139
	v_cvt_pk_bf16_f32 v172, v4, v5
	v_cvt_pk_bf16_f32 v173, v6, v7
	v_cvt_pk_bf16_f32 v174, v8, v9
	v_cvt_pk_bf16_f32 v175, v10, v11
	v_add_u32_e32 v95, 0x2580000, v0
	global_store_dwordx4 v95, v[172:175], s[0:1]
	s_waitcnt vmcnt(34)
	v_lshlrev_b32_e32 v12, 16, v140
	v_and_b32_e32 v140, 0xffff0000, v140
	v_lshlrev_b32_e32 v13, 16, v141
	v_and_b32_e32 v141, 0xffff0000, v141
	v_lshlrev_b32_e32 v14, 16, v142
	v_and_b32_e32 v142, 0xffff0000, v142
	v_lshlrev_b32_e32 v15, 16, v143
	v_and_b32_e32 v143, 0xffff0000, v143
	v_fma_f32 v4, v167, v4, v12
	v_fma_f32 v5, v167, v5, v140
	v_fma_f32 v6, v167, v6, v13
	v_fma_f32 v7, v167, v7, v141
	v_fma_f32 v8, v167, v8, v14
	v_fma_f32 v9, v167, v9, v142
	v_fma_f32 v10, v167, v10, v15
	v_fma_f32 v11, v167, v11, v143
	v_cvt_pk_bf16_f32 v16, v4, v5
	v_cvt_pk_bf16_f32 v17, v6, v7
	v_cvt_pk_bf16_f32 v18, v8, v9
	v_cvt_pk_bf16_f32 v19, v10, v11
	v_add_u32_e32 v3, 0x2600000, v0
	global_store_dwordx4 v3, v[16:19], s[0:1]
	s_waitcnt vmcnt(33)
	v_lshlrev_b32_e32 v12, 16, v144
	v_and_b32_e32 v144, 0xffff0000, v144
	v_lshlrev_b32_e32 v13, 16, v145
	v_and_b32_e32 v145, 0xffff0000, v145
	v_lshlrev_b32_e32 v14, 16, v146
	v_and_b32_e32 v146, 0xffff0000, v146
	v_lshlrev_b32_e32 v15, 16, v147
	v_and_b32_e32 v147, 0xffff0000, v147
	v_fma_f32 v4, v168, v4, v12
	v_fma_f32 v5, v168, v5, v144
	v_fma_f32 v6, v168, v6, v13
	v_fma_f32 v7, v168, v7, v145
	v_fma_f32 v8, v168, v8, v14
	v_fma_f32 v9, v168, v9, v146
	v_fma_f32 v10, v168, v10, v15
	v_fma_f32 v11, v168, v11, v147
	v_cvt_pk_bf16_f32 v172, v4, v5
	v_cvt_pk_bf16_f32 v173, v6, v7
	v_cvt_pk_bf16_f32 v174, v8, v9
	v_cvt_pk_bf16_f32 v175, v10, v11
	v_add_u32_e32 v95, 0x2680000, v0
	global_store_dwordx4 v95, v[172:175], s[0:1]
	s_waitcnt vmcnt(32)
	v_lshlrev_b32_e32 v12, 16, v148
	v_and_b32_e32 v148, 0xffff0000, v148
	v_lshlrev_b32_e32 v13, 16, v149
	v_and_b32_e32 v149, 0xffff0000, v149
	v_lshlrev_b32_e32 v14, 16, v150
	v_and_b32_e32 v150, 0xffff0000, v150
	v_lshlrev_b32_e32 v15, 16, v151
	v_and_b32_e32 v151, 0xffff0000, v151
	v_fma_f32 v4, v169, v4, v12
	v_fma_f32 v5, v169, v5, v148
	v_fma_f32 v6, v169, v6, v13
	v_fma_f32 v7, v169, v7, v149
	v_fma_f32 v8, v169, v8, v14
	v_fma_f32 v9, v169, v9, v150
	v_fma_f32 v10, v169, v10, v15
	v_fma_f32 v11, v169, v11, v151
	v_cvt_pk_bf16_f32 v16, v4, v5
	v_cvt_pk_bf16_f32 v17, v6, v7
	v_cvt_pk_bf16_f32 v18, v8, v9
	v_cvt_pk_bf16_f32 v19, v10, v11
	v_add_u32_e32 v3, 0x2700000, v0
	global_store_dwordx4 v3, v[16:19], s[0:1]
	s_waitcnt vmcnt(31)
	v_lshlrev_b32_e32 v12, 16, v152
	v_and_b32_e32 v152, 0xffff0000, v152
	v_lshlrev_b32_e32 v13, 16, v153
	v_and_b32_e32 v153, 0xffff0000, v153
	v_lshlrev_b32_e32 v14, 16, v154
	v_and_b32_e32 v154, 0xffff0000, v154
	v_lshlrev_b32_e32 v15, 16, v155
	v_and_b32_e32 v155, 0xffff0000, v155
	v_fma_f32 v4, v170, v4, v12
	v_fma_f32 v5, v170, v5, v152
	v_fma_f32 v6, v170, v6, v13
	v_fma_f32 v7, v170, v7, v153
	v_fma_f32 v8, v170, v8, v14
	v_fma_f32 v9, v170, v9, v154
	v_fma_f32 v10, v170, v10, v15
	v_fma_f32 v11, v170, v11, v155
	v_cvt_pk_bf16_f32 v172, v4, v5
	v_cvt_pk_bf16_f32 v173, v6, v7
	v_cvt_pk_bf16_f32 v174, v8, v9
	v_cvt_pk_bf16_f32 v175, v10, v11
	v_add_u32_e32 v95, 0x2780000, v0
	global_store_dwordx4 v95, v[172:175], s[0:1]
